# combo13 + P1 first-operand rows: the 16 gain / modulation vector loads of a row requested next to its x loads (one L2 round trip instead of 8 drained pairs per row)
# speedup vs baseline: 1.0043x; 1.0043x over previous
; #define GAS __attribute__((address_space(1)))
; __device__ __forceinline__ unsigned cvt_pk_bf16(float lo, float hi) { unsigned r; asm volatile("v_cvt_pk_bf16_f32 %0, %1, %2" : "=v"(r) : "v"(lo), "v"(hi)); return r; }
; __device__ __forceinline__ void phase_weights(LAS unsigned char* lds, const Ptrs& P, int wg, int G, int wv) {
;     ...
;             for (int j = 0; j < 4; ++j) {
;                 const int cidx = 8 * lane + 512 * j;
;                 u32x4 w; unsigned w8[2] = {0u, 0u};
; #pragma unroll
;                 for (int h = 0; h < 2; ++h) {
;                     const f32x4 a = *(const GAS f32x4*)((const GAS float*)P.norm_ffn1 + cidx + 4 * h) * (*(const GAS f32x4*)((const GAS float*)mods + (size_t)b * MODS_LD + D + cidx + 4 * h) + 1.0f);
;                     const f32x4 o = v[j][h] * a;
;                     if (h == 0) { w.x = cvt_pk_bf16(o[0], o[1]); w.y = cvt_pk_bf16(o[2], o[3]); } else { w.z = cvt_pk_bf16(o[0], o[1]); w.w = cvt_pk_bf16(o[2], o[3]); }
;                     if (USE_I8) { const f32x4 oq = o * sr8; w8[h] = cvt_i8x4(oq[0], oq[1], oq[2], oq[3]); }
;                 }
;                 if (!USE_I8) *(GAS u32x4*)(xa + pg8::img_chunk(r, cidx >> 3, KT_D)) = w;
;                 else { const int rr = r & 15; u32x2 ww; ww.x = w8[0]; ww.y = w8[1];
;                     *(GAS u32x2*)((GAS char*)(ws + WS_XA8) + ((size_t)(r >> 7) * KT_D8 + (cidx >> 7)) * pg8::HTB + (size_t)((((r >> 4) & 7) * 2 + ((cidx >> 6) & 1)) * 1024 + ((rr * 64 + (cidx & 63)) ^ ((rr >> 3) << 5)))) = ww; }
.LBB0_81:
	s_or_b64 exec, exec, s[6:7]
	s_waitcnt vmcnt(0)
	s_ashr_i32 s6, s30, 12
	s_mul_hi_i32 s7, s6, 0x12000
	s_mul_i32 s6, s6, 0x12000
	s_add_u32 s6, s33, s6
	s_addc_u32 s7, s38, s7
	s_add_u32 s26, s6, 0x2000
	s_addc_u32 s27, s7, 0
	s_nop 1
	v_mov_b32_e32 v60, v180
	v_mov_b32_e32 v61, v181
	v_mov_b32_e32 v62, v182
	v_mov_b32_e32 v63, v183
	s_nop 1
	v_mov_b32_e32 v64, v212
	v_mov_b32_e32 v65, v213
	v_mov_b32_e32 v66, v214
	v_mov_b32_e32 v67, v215
	s_ashr_i32 s6, s30, 7
	s_and_b32 s36, s30, 15
	s_ashr_i32 s7, s6, 31
	v_lshl_add_u64 v[48:49], v[48:49], 0, s[10:11]
	v_lshl_add_u64 v[50:51], v[50:51], 0, s[24:25]
	v_pk_add_f32 v[62:63], v[62:63], 1.0 op_sel_hi:[1,0]
	v_pk_add_f32 v[60:61], v[60:61], 1.0 op_sel_hi:[1,0]
	v_pk_mul_f32 v[62:63], v[66:67], v[62:63]
	v_pk_mul_f32 v[60:61], v[64:65], v[60:61]
	v_pk_mul_f32 v[68:69], v[30:31], v[62:63]
	v_pk_mul_f32 v[70:71], v[28:29], v[60:61]
	v_lshl_or_b32 v30, s36, 6, v53
	v_cvt_pk_bf16_f32 v28, v70, v71
	s_lshl_b64 s[36:37], s[6:7], 18
	v_cvt_pk_bf16_f32 v28, v68, v69
	s_nop 1
	v_mov_b32_e32 v60, v184
	v_mov_b32_e32 v61, v185
	v_mov_b32_e32 v62, v186
	v_mov_b32_e32 v63, v187
	s_nop 1
	v_mov_b32_e32 v64, v216
	v_mov_b32_e32 v65, v217
	v_mov_b32_e32 v66, v218
	v_mov_b32_e32 v67, v219
	v_fmamk_f32 v28, v32, 0x3a000000, v54
	v_mul_f32_e32 v29, 0x4f800000, v28
	v_cmp_gt_f32_e32 vcc, s9, v28
	s_add_u32 s36, s31, s36
	s_addc_u32 s37, s34, s37
	v_cndmask_b32_e32 v28, v28, v29, vcc
	v_sqrt_f32_e32 v29, v28
	s_lshr_b32 s39, s30, 3
	s_lshl_b32 s40, s30, 2
	s_add_i32 s30, s30, s8
	v_add_u32_e32 v31, -1, v29
	v_add_u32_e32 v32, 1, v29
	v_fma_f32 v72, -v31, v29, v28
	v_fma_f32 v73, -v32, v29, v28
	v_cmp_ge_f32_e64 s[6:7], 0, v72
	v_pk_add_f32 v[60:61], v[60:61], 1.0 op_sel_hi:[1,0]
	v_cndmask_b32_e64 v29, v29, v31, s[6:7]
	v_cmp_lt_f32_e64 s[6:7], 0, v73
	v_and_or_b32 v31, s39, 14, v52
	v_lshlrev_b32_e32 v31, 10, v31
	v_cndmask_b32_e64 v29, v29, v32, s[6:7]
	v_mul_f32_e32 v32, 0x37800000, v29
	s_and_b32 s6, s40, 32
	v_cndmask_b32_e32 v29, v29, v32, vcc
	v_cmp_class_f32_e32 vcc, v28, v55
	v_bitop3_b32 v32, v31, v30, s6 bitop3:0xf6
	v_pk_add_f32 v[62:63], v[62:63], 1.0 op_sel_hi:[1,0]
	v_cndmask_b32_e32 v30, v29, v28, vcc
	v_mul_f32_e32 v30, 0x40c00000, v30
	v_div_scale_f32 v31, s[6:7], v30, v30, s35
	v_lshl_add_u64 v[28:29], s[36:37], 0, v[32:33]
	v_rcp_f32_e32 v32, v31
	v_div_scale_f32 v74, vcc, s35, v30, s35
	v_pk_mul_f32 v[60:61], v[64:65], v[60:61]
	v_fma_f32 v75, -v31, v32, 1.0
	v_fmac_f32_e32 v32, v75, v32
	v_mul_f32_e32 v75, v74, v32
	v_fma_f32 v76, -v31, v75, v74
	v_fmac_f32_e32 v75, v76, v32
	v_fma_f32 v31, -v31, v75, v74
	v_div_fmas_f32 v31, v31, v32, v75
	v_div_fixup_f32 v30, v31, v30, s35
	v_pk_mul_f32 v[70:71], v[30:31], v[70:71] op_sel_hi:[0,1]
	v_pk_mul_f32 v[68:69], v[30:31], v[68:69] op_sel_hi:[0,1]
	v_add_f32_e32 v31, 0x43000000, v70
	v_add_f32_e32 v32, 0x43000000, v71
	v_cvt_pk_u8_f32 v31, v31, 0, 0
	v_add_f32_e32 v68, 0x43000000, v68
	v_cvt_pk_u8_f32 v31, v32, 1, v31
	v_add_f32_e32 v69, 0x43000000, v69
	v_cvt_pk_u8_f32 v31, v68, 2, v31
	v_cvt_pk_u8_f32 v31, v69, 3, v31
	v_pk_mul_f32 v[62:63], v[66:67], v[62:63]
	v_pk_mul_f32 v[24:25], v[24:25], v[60:61]
	v_xor_b32_e32 v68, 0x80808080, v31
	v_pk_mul_f32 v[26:27], v[26:27], v[62:63]
	v_cvt_pk_bf16_f32 v31, v24, v25
	v_lshl_add_u64 v[72:73], v[28:29], 0, v[34:35]
	v_cvt_pk_bf16_f32 v31, v26, v27
	v_lshl_add_u64 v[64:65], v[28:29], 0, v[36:37]
	v_pk_mul_f32 v[24:25], v[30:31], v[24:25] op_sel_hi:[0,1]
	v_add_f32_e32 v24, 0x43000000, v24
	v_pk_mul_f32 v[26:27], v[30:31], v[26:27] op_sel_hi:[0,1]
	v_add_f32_e32 v25, 0x43000000, v25
	v_cvt_pk_u8_f32 v24, v24, 0, 0
	v_add_f32_e32 v26, 0x43000000, v26
	v_cvt_pk_u8_f32 v24, v25, 1, v24
	v_add_f32_e32 v27, 0x43000000, v27
	v_cvt_pk_u8_f32 v24, v26, 2, v24
	v_cvt_pk_u8_f32 v24, v27, 3, v24
	v_xor_b32_e32 v69, 0x80808080, v24
	global_store_dwordx2 v[72:73], v[68:69], off
	s_nop 1
	v_mov_b32_e32 v24, v188
	v_mov_b32_e32 v25, v189
	v_mov_b32_e32 v26, v190
	v_mov_b32_e32 v27, v191
	s_nop 1
	v_mov_b32_e32 v60, v220
	v_mov_b32_e32 v61, v221
	v_mov_b32_e32 v62, v222
	v_mov_b32_e32 v63, v223
	s_cmpk_gt_i32 s30, 0x3fff
	v_pk_add_f32 v[26:27], v[26:27], 1.0 op_sel_hi:[1,0]
	v_pk_add_f32 v[24:25], v[24:25], 1.0 op_sel_hi:[1,0]
	v_pk_mul_f32 v[26:27], v[62:63], v[26:27]
	v_pk_mul_f32 v[24:25], v[60:61], v[24:25]
	v_pk_mul_f32 v[60:61], v[22:23], v[26:27]
	v_pk_mul_f32 v[62:63], v[20:21], v[24:25]
	s_nop 0
	v_cvt_pk_bf16_f32 v20, v62, v63
	v_pk_mul_f32 v[62:63], v[30:31], v[62:63] op_sel_hi:[0,1]
	v_cvt_pk_bf16_f32 v20, v60, v61
	s_nop 1
	v_mov_b32_e32 v20, v192
	v_mov_b32_e32 v21, v193
	v_mov_b32_e32 v22, v194
	v_mov_b32_e32 v23, v195
	s_nop 1
	v_mov_b32_e32 v24, v224
	v_mov_b32_e32 v25, v225
	v_mov_b32_e32 v26, v226
	v_mov_b32_e32 v27, v227
	v_pk_mul_f32 v[60:61], v[30:31], v[60:61] op_sel_hi:[0,1]
	v_add_f32_e32 v31, 0x43000000, v62
	v_add_f32_e32 v32, 0x43000000, v63
	v_cvt_pk_u8_f32 v31, v31, 0, 0
	v_add_f32_e32 v60, 0x43000000, v60
	v_cvt_pk_u8_f32 v31, v32, 1, v31
	v_add_f32_e32 v61, 0x43000000, v61
	v_cvt_pk_u8_f32 v31, v60, 2, v31
	v_cvt_pk_u8_f32 v31, v61, 3, v31
	v_xor_b32_e32 v60, 0x80808080, v31
	v_pk_add_f32 v[20:21], v[20:21], 1.0 op_sel_hi:[1,0]
	v_pk_mul_f32 v[20:21], v[24:25], v[20:21]
	v_pk_add_f32 v[22:23], v[22:23], 1.0 op_sel_hi:[1,0]
	v_pk_mul_f32 v[16:17], v[16:17], v[20:21]
	v_pk_mul_f32 v[22:23], v[26:27], v[22:23]
	v_cvt_pk_bf16_f32 v20, v16, v17
	v_pk_mul_f32 v[16:17], v[30:31], v[16:17] op_sel_hi:[0,1]
	v_pk_mul_f32 v[18:19], v[18:19], v[22:23]
	v_add_f32_e32 v16, 0x43000000, v16
	v_cvt_pk_bf16_f32 v20, v18, v19
	v_pk_mul_f32 v[18:19], v[30:31], v[18:19] op_sel_hi:[0,1]
; #define GAS __attribute__((address_space(1)))
; __device__ __forceinline__ unsigned cvt_pk_bf16(float lo, float hi) { unsigned r; asm volatile("v_cvt_pk_bf16_f32 %0, %1, %2" : "=v"(r) : "v"(lo), "v"(hi)); return r; }
; __device__ __forceinline__ void phase_weights(LAS unsigned char* lds, const Ptrs& P, int wg, int G, int wv) {
;     ...
;             for (int j = 0; j < 4; ++j) {
;                 const int cidx = 8 * lane + 512 * j;
;                 u32x4 w; unsigned w8[2] = {0u, 0u};
; #pragma unroll
;                 for (int h = 0; h < 2; ++h) {
;                     const f32x4 a = *(const GAS f32x4*)((const GAS float*)P.norm_ffn1 + cidx + 4 * h) * (*(const GAS f32x4*)((const GAS float*)mods + (size_t)b * MODS_LD + D + cidx + 4 * h) + 1.0f);
;                     const f32x4 o = v[j][h] * a;
;                     if (h == 0) { w.x = cvt_pk_bf16(o[0], o[1]); w.y = cvt_pk_bf16(o[2], o[3]); } else { w.z = cvt_pk_bf16(o[0], o[1]); w.w = cvt_pk_bf16(o[2], o[3]); }
;                     if (USE_I8) { const f32x4 oq = o * sr8; w8[h] = cvt_i8x4(oq[0], oq[1], oq[2], oq[3]); }
;                 }
;                 if (!USE_I8) *(GAS u32x4*)(xa + pg8::img_chunk(r, cidx >> 3, KT_D)) = w;
;                 else { const int rr = r & 15; u32x2 ww; ww.x = w8[0]; ww.y = w8[1];
;                     *(GAS u32x2*)((GAS char*)(ws + WS_XA8) + ((size_t)(r >> 7) * KT_D8 + (cidx >> 7)) * pg8::HTB + (size_t)((((r >> 4) & 7) * 2 + ((cidx >> 6) & 1)) * 1024 + ((rr * 64 + (cidx & 63)) ^ ((rr >> 3) << 5)))) = ww; }
	v_add_f32_e32 v17, 0x43000000, v17
	v_cvt_pk_u8_f32 v16, v16, 0, 0
	v_add_f32_e32 v18, 0x43000000, v18
	v_cvt_pk_u8_f32 v16, v17, 1, v16
	v_add_f32_e32 v19, 0x43000000, v19
	v_cvt_pk_u8_f32 v16, v18, 2, v16
	v_cvt_pk_u8_f32 v16, v19, 3, v16
	v_xor_b32_e32 v61, 0x80808080, v16
	global_store_dwordx2 v[64:65], v[60:61], off
	s_nop 1
	v_mov_b32_e32 v16, v196
	v_mov_b32_e32 v17, v197
	v_mov_b32_e32 v18, v198
	v_mov_b32_e32 v19, v199
	s_nop 1
	v_mov_b32_e32 v20, v228
	v_mov_b32_e32 v21, v229
	v_mov_b32_e32 v22, v230
	v_mov_b32_e32 v23, v231
	v_lshl_add_u64 v[24:25], v[28:29], 0, v[38:39]
	v_pk_add_f32 v[18:19], v[18:19], 1.0 op_sel_hi:[1,0]
	v_pk_add_f32 v[16:17], v[16:17], 1.0 op_sel_hi:[1,0]
	v_pk_mul_f32 v[18:19], v[22:23], v[18:19]
	v_pk_mul_f32 v[16:17], v[20:21], v[16:17]
	v_pk_mul_f32 v[20:21], v[14:15], v[18:19]
	v_pk_mul_f32 v[22:23], v[12:13], v[16:17]
	s_nop 0
	v_cvt_pk_bf16_f32 v12, v22, v23
	v_pk_mul_f32 v[22:23], v[30:31], v[22:23] op_sel_hi:[0,1]
	v_cvt_pk_bf16_f32 v12, v20, v21
	s_nop 1
	v_mov_b32_e32 v12, v200
	v_mov_b32_e32 v13, v201
	v_mov_b32_e32 v14, v202
	v_mov_b32_e32 v15, v203
	s_nop 1
	v_mov_b32_e32 v16, v232
	v_mov_b32_e32 v17, v233
	v_mov_b32_e32 v18, v234
	v_mov_b32_e32 v19, v235
	v_add_f32_e32 v22, 0x43000000, v22
	v_pk_mul_f32 v[20:21], v[30:31], v[20:21] op_sel_hi:[0,1]
	v_add_f32_e32 v23, 0x43000000, v23
	v_cvt_pk_u8_f32 v22, v22, 0, 0
	v_add_f32_e32 v20, 0x43000000, v20
	v_cvt_pk_u8_f32 v22, v23, 1, v22
	v_add_f32_e32 v21, 0x43000000, v21
	v_cvt_pk_u8_f32 v20, v20, 2, v22
	v_cvt_pk_u8_f32 v20, v21, 3, v20
	v_xor_b32_e32 v20, 0x80808080, v20
	v_pk_add_f32 v[12:13], v[12:13], 1.0 op_sel_hi:[1,0]
	v_pk_mul_f32 v[12:13], v[16:17], v[12:13]
	v_pk_add_f32 v[14:15], v[14:15], 1.0 op_sel_hi:[1,0]
	v_pk_mul_f32 v[8:9], v[8:9], v[12:13]
	v_pk_mul_f32 v[14:15], v[18:19], v[14:15]
	v_cvt_pk_bf16_f32 v12, v8, v9
	v_pk_mul_f32 v[8:9], v[30:31], v[8:9] op_sel_hi:[0,1]
	v_pk_mul_f32 v[10:11], v[10:11], v[14:15]
	v_add_f32_e32 v8, 0x43000000, v8
	v_cvt_pk_bf16_f32 v12, v10, v11
	v_pk_mul_f32 v[10:11], v[30:31], v[10:11] op_sel_hi:[0,1]
	v_add_f32_e32 v9, 0x43000000, v9
	v_cvt_pk_u8_f32 v8, v8, 0, 0
	v_add_f32_e32 v10, 0x43000000, v10
	v_cvt_pk_u8_f32 v8, v9, 1, v8
	v_add_f32_e32 v11, 0x43000000, v11
	v_cvt_pk_u8_f32 v8, v10, 2, v8
	v_cvt_pk_u8_f32 v8, v11, 3, v8
	v_xor_b32_e32 v21, 0x80808080, v8
	global_store_dwordx2 v[24:25], v[20:21], off
	s_nop 1
	v_mov_b32_e32 v8, v204
	v_mov_b32_e32 v9, v205
	v_mov_b32_e32 v10, v206
	v_mov_b32_e32 v11, v207
	s_nop 1
	v_mov_b32_e32 v12, v236
	v_mov_b32_e32 v13, v237
	v_mov_b32_e32 v14, v238
	v_mov_b32_e32 v15, v239
	v_lshl_add_u64 v[16:17], v[28:29], 0, v[40:41]
	v_pk_add_f32 v[10:11], v[10:11], 1.0 op_sel_hi:[1,0]
	v_pk_add_f32 v[8:9], v[8:9], 1.0 op_sel_hi:[1,0]
	v_pk_mul_f32 v[10:11], v[14:15], v[10:11]
	v_pk_mul_f32 v[8:9], v[12:13], v[8:9]
	v_pk_mul_f32 v[12:13], v[6:7], v[10:11]
	v_pk_mul_f32 v[14:15], v[4:5], v[8:9]
	s_nop 0
	v_cvt_pk_bf16_f32 v4, v14, v15
	v_pk_mul_f32 v[14:15], v[30:31], v[14:15] op_sel_hi:[0,1]
	v_cvt_pk_bf16_f32 v4, v12, v13
	s_nop 1
	v_mov_b32_e32 v4, v208
	v_mov_b32_e32 v5, v209
	v_mov_b32_e32 v6, v210
	v_mov_b32_e32 v7, v211
	s_nop 1
	v_mov_b32_e32 v8, v240
	v_mov_b32_e32 v9, v241
	v_mov_b32_e32 v10, v242
	v_mov_b32_e32 v11, v243
	v_add_f32_e32 v14, 0x43000000, v14
	v_pk_mul_f32 v[12:13], v[30:31], v[12:13] op_sel_hi:[0,1]
	v_add_f32_e32 v15, 0x43000000, v15
	v_cvt_pk_u8_f32 v14, v14, 0, 0
	v_add_f32_e32 v12, 0x43000000, v12
	v_cvt_pk_u8_f32 v14, v15, 1, v14
	v_add_f32_e32 v13, 0x43000000, v13
	v_cvt_pk_u8_f32 v12, v12, 2, v14
	v_cvt_pk_u8_f32 v12, v13, 3, v12
	v_xor_b32_e32 v12, 0x80808080, v12
	v_pk_add_f32 v[4:5], v[4:5], 1.0 op_sel_hi:[1,0]
	v_pk_mul_f32 v[4:5], v[8:9], v[4:5]
	v_pk_add_f32 v[6:7], v[6:7], 1.0 op_sel_hi:[1,0]
	v_pk_mul_f32 v[0:1], v[0:1], v[4:5]
	v_pk_mul_f32 v[6:7], v[10:11], v[6:7]
	v_cvt_pk_bf16_f32 v4, v0, v1
	v_pk_mul_f32 v[0:1], v[30:31], v[0:1] op_sel_hi:[0,1]
	v_pk_mul_f32 v[2:3], v[2:3], v[6:7]
	v_add_f32_e32 v0, 0x43000000, v0
	v_cvt_pk_bf16_f32 v4, v2, v3
	v_pk_mul_f32 v[2:3], v[30:31], v[2:3] op_sel_hi:[0,1]
	v_add_f32_e32 v1, 0x43000000, v1
	v_cvt_pk_u8_f32 v0, v0, 0, 0
	v_add_f32_e32 v2, 0x43000000, v2
	v_cvt_pk_u8_f32 v0, v1, 1, v0
	v_add_f32_e32 v3, 0x43000000, v3
	v_cvt_pk_u8_f32 v0, v2, 2, v0
	v_cvt_pk_u8_f32 v0, v3, 3, v0
	v_xor_b32_e32 v13, 0x80808080, v0
	global_store_dwordx2 v[16:17], v[12:13], off
	s_cbranch_scc1 .LBB0_84
; #define GAS __attribute__((address_space(1)))
; __device__ __forceinline__ void phase_weights(LAS unsigned char* lds, const Ptrs& P, int wg, int G, int wv) {
;     ...
;             const GAS float* xr = (const GAS float*)P.x + (size_t)r * D + 8 * lane;
;             f32x4 v[4][2]; float ss = 0.f;
; #pragma unroll
;             for (int j = 0; j < 4; ++j)
; #pragma unroll
;                 for (int h = 0; h < 2; ++h) { v[j][h] = *(const GAS f32x4*)(xr + 512 * j + 4 * h); ss += (v[j][h][0] * v[j][h][0] + v[j][h][1] * v[j][h][1]) + (v[j][h][2] * v[j][h][2] + v[j][h][3] * v[j][h][3]); }
;             ss = wave_sum(ss);
;             if (lane < 8) rowss0[(size_t)r * 8 + lane] = lane == 0 ? ss : 0.f;
.LBB0_82:
	global_load_dwordx4 v[28:31], v[50:51], off offset:-4096
	global_load_dwordx4 v[24:27], v[50:51], off offset:-4080
	global_load_dwordx4 v[20:23], v[50:51], off offset:-2048
	global_load_dwordx4 v[16:19], v[50:51], off offset:-2032
	global_load_dwordx4 v[12:15], v[50:51], off
	global_load_dwordx4 v[8:11], v[50:51], off offset:16
	global_load_dwordx4 v[4:7], v[50:51], off offset:2048
	global_load_dwordx4 v[0:3], v[50:51], off offset:2064
	s_ashr_i32 s6, s30, 12
	s_mul_hi_i32 s7, s6, 0x12000
	s_mul_i32 s6, s6, 0x12000
	s_add_u32 s6, s33, s6
	s_addc_u32 s7, s38, s7
	s_add_u32 s26, s6, 0x2000
	s_addc_u32 s27, s7, 0
	global_load_dwordx4 v[180:183], v56, s[26:27]
	global_load_dwordx4 v[212:215], v[42:43], off
	global_load_dwordx4 v[184:187], v56, s[26:27] offset:16
	global_load_dwordx4 v[216:219], v[42:43], off offset:16
	global_load_dwordx4 v[188:191], v57, s[26:27]
	global_load_dwordx4 v[220:223], v[42:43], off offset:2048
	global_load_dwordx4 v[192:195], v57, s[26:27] offset:16
	global_load_dwordx4 v[224:227], v[42:43], off offset:2064
	global_load_dwordx4 v[196:199], v58, s[26:27]
	global_load_dwordx4 v[228:231], v[44:45], off
	global_load_dwordx4 v[200:203], v58, s[26:27] offset:16
	global_load_dwordx4 v[232:235], v[44:45], off offset:16
	global_load_dwordx4 v[204:207], v59, s[26:27]
	global_load_dwordx4 v[236:239], v[46:47], off
	global_load_dwordx4 v[208:211], v59, s[26:27] offset:16
	global_load_dwordx4 v[240:243], v[46:47], off offset:16
	v_mbcnt_lo_u32_b32 v32, -1, 0
	v_mbcnt_hi_u32_b32 v32, -1, v32
	s_waitcnt vmcnt(23)
	v_mul_f32_e32 v60, v29, v29
	v_mul_f32_e32 v61, v31, v31
	s_waitcnt vmcnt(22)
	v_mul_f32_e32 v62, v25, v25
	v_mul_f32_e32 v63, v27, v27
	s_waitcnt vmcnt(21)
	v_mul_f32_e32 v64, v21, v21
	v_mul_f32_e32 v65, v23, v23
	v_fmac_f32_e32 v60, v28, v28
	v_fmac_f32_e32 v61, v30, v30
	v_fmac_f32_e32 v62, v24, v24
	v_fmac_f32_e32 v63, v26, v26
	s_waitcnt vmcnt(20)
	v_mul_f32_e32 v66, v17, v17
	v_mul_f32_e32 v67, v19, v19
	v_fmac_f32_e32 v64, v20, v20
	v_fmac_f32_e32 v65, v22, v22
	v_add_f32_e32 v60, v60, v61
	v_add_f32_e32 v61, v62, v63
	s_waitcnt vmcnt(19)
	v_mul_f32_e32 v68, v13, v13
	v_mul_f32_e32 v69, v15, v15
	v_fmac_f32_e32 v66, v16, v16
	v_fmac_f32_e32 v67, v18, v18
	v_add_f32_e32 v62, v64, v65
	v_add_f32_e32 v60, v60, v61
	s_waitcnt vmcnt(18)
	v_mul_f32_e32 v70, v9, v9
	v_mul_f32_e32 v71, v11, v11
	v_fmac_f32_e32 v68, v12, v12
	v_fmac_f32_e32 v69, v14, v14
	v_add_f32_e32 v63, v66, v67
	v_add_f32_e32 v60, v60, v62
	s_waitcnt vmcnt(17)
	v_mul_f32_e32 v72, v5, v5
	v_mul_f32_e32 v73, v7, v7
	v_fmac_f32_e32 v70, v8, v8
	v_fmac_f32_e32 v71, v10, v10
	v_add_f32_e32 v64, v68, v69
	v_add_f32_e32 v60, v60, v63
	s_waitcnt vmcnt(16)
	v_mul_f32_e32 v74, v1, v1
	v_mul_f32_e32 v75, v3, v3
	v_fmac_f32_e32 v72, v4, v4
	v_fmac_f32_e32 v73, v6, v6
	v_add_f32_e32 v65, v70, v71
	v_add_f32_e32 v60, v60, v64
	v_fmac_f32_e32 v74, v0, v0
	v_fmac_f32_e32 v75, v2, v2
	v_add_f32_e32 v66, v72, v73
	v_add_f32_e32 v60, v60, v65
	v_lshlrev_b32_e32 v32, 2, v32
	v_add_f32_e32 v67, v74, v75
	v_add_f32_e32 v60, v60, v66
	v_xor_b32_e32 v32, 4, v32
	v_add_f32_e32 v60, v60, v67
	ds_bpermute_b32 v32, v32, v60
	v_mbcnt_lo_u32_b32 v61, -1, 0
	v_mbcnt_hi_u32_b32 v61, -1, v61
	s_waitcnt lgkmcnt(0)
	v_add_f32_e32 v32, v60, v32
	v_lshlrev_b32_e32 v61, 2, v61
	v_xor_b32_e32 v61, 8, v61
	ds_bpermute_b32 v60, v61, v32
	v_mbcnt_lo_u32_b32 v61, -1, 0
	v_mbcnt_hi_u32_b32 v61, -1, v61
	s_waitcnt lgkmcnt(0)
	v_add_f32_e32 v32, v32, v60
	v_lshlrev_b32_e32 v61, 2, v61
	v_xor_b32_e32 v61, 16, v61
	ds_bpermute_b32 v60, v61, v32
	v_mbcnt_lo_u32_b32 v61, -1, 0
	v_mbcnt_hi_u32_b32 v61, -1, v61
	s_waitcnt lgkmcnt(0)
	v_add_f32_e32 v32, v32, v60
	v_lshlrev_b32_e32 v61, 2, v61
	v_xor_b32_e32 v61, 32, v61
	ds_bpermute_b32 v60, v61, v32
	v_mbcnt_lo_u32_b32 v61, -1, 0
	v_mbcnt_hi_u32_b32 v61, -1, v61
	s_waitcnt lgkmcnt(0)
	v_add_f32_e32 v32, v32, v60
	v_lshlrev_b32_e32 v61, 2, v61
	v_xor_b32_e32 v61, 64, v61
	ds_bpermute_b32 v60, v61, v32
	v_mbcnt_lo_u32_b32 v61, -1, 0
	v_mbcnt_hi_u32_b32 v61, -1, v61
	s_waitcnt lgkmcnt(0)
	v_add_f32_e32 v32, v32, v60
	v_lshlrev_b32_e32 v61, 2, v61
	v_xor_b32_e32 v60, 0x80, v61
	ds_bpermute_b32 v60, v60, v32
	s_waitcnt lgkmcnt(0)
	v_add_f32_e32 v32, v32, v60
	s_and_saveexec_b64 s[6:7], s[0:1]
	s_cbranch_execz .LBB0_81
	v_cndmask_b32_e64 v60, 0, v32, s[4:5]
	global_store_dword v[48:49], v60, off
	s_branch .LBB0_81
